# phase-3 low-rank GEMM runs only the two k-steps that carry data (the other 128 of K=256 columns are zero padding)
# baseline (speedup 1.0000x reference)
.LBB0_456:
	s_mov_b64 s[14:15], 0x80
	s_add_i32 m0, s69, 0x18000
	v_lshl_add_u64 v[12:13], v[12:13], 0, s[14:15]
	s_waitcnt vmcnt(4)
	s_barrier
	global_load_lds_dwordx4 v[12:13], off
	v_lshl_add_u64 v[10:11], v[10:11], 0, s[14:15]
	s_add_i32 m0, s69, 0x1a000
	s_add_i32 s75, s69, 0x8000
	global_load_lds_dwordx4 v[10:11], off
	v_lshl_add_u64 v[8:9], v[8:9], 0, s[14:15]
	s_mov_b32 m0, s75
	s_add_i32 s76, s69, 0xa000
	global_load_lds_dwordx4 v[8:9], off
	v_lshl_add_u64 v[6:7], v[6:7], 0, s[14:15]
	s_mov_b32 m0, s76
	v_lshl_add_u64 v[4:5], v[4:5], 0, s[14:15]
	global_load_lds_dwordx4 v[6:7], off
	s_add_i32 m0, s69, 0x1c000
	v_lshl_add_u64 v[2:3], v[2:3], 0, s[14:15]
	global_load_lds_dwordx4 v[4:5], off
	s_add_i32 m0, s69, 0x1e000
	s_lshr_b32 s1, s1, 26
	global_load_lds_dwordx4 v[2:3], off
	v_lshrrev_b32_e32 v3, 1, v16
	v_and_b32_e32 v3, 24, v3
	v_and_b32_e32 v2, 15, v16
	v_lshlrev_b32_e32 v4, 1, v3
	s_add_i32 s1, s0, s1
	v_lshl_or_b32 v1, s5, 6, v2
	v_lshl_or_b32 v2, v2, 6, v4
	v_lshlrev_b32_e32 v4, 2, v16
	s_ashr_i32 s77, s1, 6
	s_mov_b32 s77, 2
	s_lshl_b32 s1, s5, 13
	v_and_b32_e32 v4, 32, v4
	v_bitop3_b32 v5, v2, s1, v4 bitop3:0xde
	s_lshl_b32 s1, s6, 5
	s_and_b32 s1, s1, 0x60
	s_sext_i32_i8 s87, s4
	s_lshl_b32 s4, s1, 7
	v_bitop3_b32 v158, v2, s4, v4 bitop3:0xde
	v_add_u32_e32 v2, v17, v14
	v_or_b32_e32 v159, s1, v3
	v_add_lshl_u32 v2, v2, v15, 1
	v_mov_b32_e32 v3, v133
	s_waitcnt vmcnt(6)
	s_cmp_gt_i32 s0, 63
	v_lshl_add_u64 v[138:139], s[10:11], 0, v[2:3]
	v_add_u32_e32 v2, v20, v18
	s_cselect_b64 s[46:47], -1, 0
	v_add_lshl_u32 v2, v2, v19, 1
	s_add_i32 s81, 0, 0x10000
	s_add_i32 s82, 0, 0x14000
	s_add_i32 s78, s77, -2
	s_ashr_i32 s79, s18, 31
	s_mov_b32 s80, s18
	v_lshl_add_u64 v[140:141], s[10:11], 0, v[2:3]
	v_mov_b64_e32 v[142:143], 0x200
	v_mov_b64_e32 v[144:145], 0x1ff
	v_add_u32_e32 v160, s81, v158
	v_add_u32_e32 v161, 0, v5
	v_add_u32_e32 v162, s82, v158
	s_mov_b32 s83, 0x1721f000
	s_barrier
	s_branch .LBB0_458
